# combo16: combo15 + prenorm_rows loop: scale loads issued with the row loads at the top of the iteration (off the dependent chain), rss store deferred behind the row stores
# speedup vs baseline: 1.0130x; 1.0130x over previous
; __device__ __forceinline__ int opaque_tid() { int t = threadIdx.x; asm volatile("" : "+v"(t)); return t; }
; __device__ __forceinline__ unsigned pk2(float lo, float hi) { const f32x2 v = {lo, hi}; return __builtin_bit_cast(unsigned, __builtin_convertvector(v, hwbf16x2)); }
; __device__ __forceinline__ void prenorm_rows(const float* __restrict__ xin, bf16_t* __restrict__ an, float* __restrict__ rss, const float* __restrict__ modl, int coff) {
;     const int tid = opaque_tid(), lane = tid & 63, gw = blockIdx.x * 8 + (tid >> 6), NGW = GRID * 8;
; #pragma unroll 4
;     for (int t = gw; t < T; t += NGW) {
;         const f32x4* xr = (const f32x4*)(xin + (size_t)t * DM) + lane; f32x4 v[4]; float ss = 0.f;
; #pragma unroll
;         for (int j = 0; j < 4; ++j) { v[j] = xr[64 * j]; ss += (v[j][0] * v[j][0] + v[j][1] * v[j][1]) + (v[j][2] * v[j][2] + v[j][3] * v[j][3]); }
;         ss = wave_sum(ss); if (lane == 0) rss[t] = ss;
;         const float* mb = modl + (size_t)(t >> 13) * NMOD;
; #pragma unroll
;         for (int j = 0; j < 4; ++j) { const int col = 256 * j + 4 * lane;
;             const f32x4 sc = *(const f32x4*)(mb + coff + col);
;             const f32x4 h = v[j] * (sc + 1.0f);
;             u32x2 w; w.x = pk2(h[0], h[1]); w.y = pk2(h[2], h[3]); *(u32x2*)(an + (size_t)t * DM + col) = w; }
;     }
.LBB0_116:
	v_lshl_add_u64 v[56:57], s[90:91], 0, v[22:23]
	v_add_u32_e32 v31, 0x800, v16
	v_cmp_lt_i32_e64 s[2:3], s21, v16
	v_add_co_u32_e64 v16, s[4:5], s20, v56
	v_lshl_add_u64 v[20:21], v[20:21], 0, s[14:15]
	s_nop 0
	v_addc_co_u32_e64 v17, s[4:5], 0, v57, s[4:5]
	v_lshl_add_u64 v[22:23], v[22:23], 0, s[16:17]
	v_lshl_add_u64 v[24:25], v[24:25], 0, s[18:19]
	s_or_b64 s[8:9], s[2:3], s[8:9]
	s_waitcnt vmcnt(3)
	v_pk_add_f32 v[62:63], v[62:63], 1.0 op_sel_hi:[1,0]
	v_pk_add_f32 v[60:61], v[60:61], 1.0 op_sel_hi:[1,0]
	s_waitcnt vmcnt(2)
	v_pk_add_f32 v[66:67], v[66:67], 1.0 op_sel_hi:[1,0]
	v_pk_add_f32 v[64:65], v[64:65], 1.0 op_sel_hi:[1,0]
	s_waitcnt vmcnt(1)
	v_pk_add_f32 v[70:71], v[70:71], 1.0 op_sel_hi:[1,0]
	v_pk_add_f32 v[68:69], v[68:69], 1.0 op_sel_hi:[1,0]
	s_waitcnt vmcnt(0)
	v_pk_add_f32 v[74:75], v[74:75], 1.0 op_sel_hi:[1,0]
	v_pk_add_f32 v[72:73], v[72:73], 1.0 op_sel_hi:[1,0]
	v_pk_mul_f32 v[2:3], v[2:3], v[62:63]
	v_pk_mul_f32 v[0:1], v[0:1], v[60:61]
	v_pk_mul_f32 v[6:7], v[6:7], v[66:67]
	v_pk_mul_f32 v[4:5], v[4:5], v[64:65]
	v_pk_mul_f32 v[10:11], v[10:11], v[70:71]
	v_pk_mul_f32 v[8:9], v[8:9], v[68:69]
	v_pk_mul_f32 v[14:15], v[14:15], v[74:75]
	v_pk_mul_f32 v[12:13], v[12:13], v[72:73]
	v_cvt_pk_bf16_f32 v0, v0, v1
	v_cvt_pk_bf16_f32 v1, v2, v3
	v_cvt_pk_bf16_f32 v2, v4, v5
	v_cvt_pk_bf16_f32 v3, v6, v7
	v_cvt_pk_bf16_f32 v4, v8, v9
	v_cvt_pk_bf16_f32 v5, v10, v11
	v_cvt_pk_bf16_f32 v6, v12, v13
	v_cvt_pk_bf16_f32 v7, v14, v15
	global_store_dwordx2 v[16:17], v[0:1], off
	global_store_dwordx2 v[16:17], v[2:3], off offset:512
	global_store_dwordx2 v[16:17], v[4:5], off offset:1024
	global_store_dwordx2 v[16:17], v[6:7], off offset:1536
	s_mov_b64 s[4:5], exec
	s_and_b64 exec, exec, vcc
	global_store_dword v[86:87], v77, off
	s_mov_b64 exec, s[4:5]
	v_mov_b32_e32 v16, v31
	s_andn2_b64 exec, exec, s[8:9]
	s_cbranch_execz .LBB0_119
.LBB0_117:
	global_load_dwordx4 v[0:3], v[24:25], off
	global_load_dwordx4 v[4:7], v[24:25], off offset:1024
	global_load_dwordx4 v[8:11], v[24:25], off offset:2048
	global_load_dwordx4 v[12:15], v[24:25], off offset:3072
	v_ashrrev_i32_e32 v76, 13, v16
	v_mul_i32_i24_e32 v78, 0x1800, v76
	v_ashrrev_i32_e32 v79, 31, v78
	v_lshl_add_u64 v[78:79], v[78:79], 2, s[76:77]
	v_lshl_add_u64 v[80:81], v[78:79], 0, s[12:13]
	v_lshl_add_u64 v[82:83], v[80:81], 0, v[26:27]
	global_load_dwordx4 v[60:63], v[82:83], off
	v_lshl_add_u64 v[82:83], v[80:81], 0, v[28:29]
	global_load_dwordx4 v[64:67], v[82:83], off
	v_lshl_add_u64 v[82:83], v[80:81], 0, v[18:19]
	global_load_dwordx4 v[68:71], v[82:83], off
	v_mov_b32_e32 v84, v30
	v_mov_b32_e32 v85, v19
	v_lshl_add_u64 v[82:83], v[80:81], 0, v[84:85]
	global_load_dwordx4 v[72:75], v[82:83], off
	s_waitcnt vmcnt(7)
	v_mul_f32_e32 v17, v1, v1
	v_mul_f32_e32 v31, v3, v3
	s_waitcnt vmcnt(6)
	v_mul_f32_e32 v38, v5, v5
	v_mul_f32_e32 v39, v7, v7
	s_waitcnt vmcnt(5)
	v_mul_f32_e32 v40, v9, v9
	v_mul_f32_e32 v41, v11, v11
	v_fmac_f32_e32 v17, v0, v0
	v_fmac_f32_e32 v31, v2, v2
	v_fmac_f32_e32 v38, v4, v4
	v_fmac_f32_e32 v39, v6, v6
	s_waitcnt vmcnt(4)
	v_mul_f32_e32 v43, v13, v13
	v_mul_f32_e32 v44, v15, v15
	v_fmac_f32_e32 v40, v8, v8
	v_fmac_f32_e32 v41, v10, v10
	v_add_f32_e32 v17, v17, v31
	v_add_f32_e32 v31, v38, v39
	v_fmac_f32_e32 v43, v12, v12
	v_fmac_f32_e32 v44, v14, v14
	v_add_f32_e32 v38, v40, v41
	v_add_f32_e32 v17, v17, v31
	v_add_f32_e32 v17, v17, v38
	v_add_f32_e32 v31, v43, v44
	v_add_f32_e32 v17, v17, v31
	ds_bpermute_b32 v31, v32, v17
	s_waitcnt lgkmcnt(0)
	v_add_f32_e32 v17, v17, v31
	ds_bpermute_b32 v31, v33, v17
	s_waitcnt lgkmcnt(0)
	v_add_f32_e32 v17, v17, v31
	ds_bpermute_b32 v31, v34, v17
	s_waitcnt lgkmcnt(0)
	v_add_f32_e32 v17, v17, v31
	ds_bpermute_b32 v31, v35, v17
	s_waitcnt lgkmcnt(0)
	v_add_f32_e32 v17, v17, v31
	ds_bpermute_b32 v31, v36, v17
	s_waitcnt lgkmcnt(0)
	v_add_f32_e32 v17, v17, v31
	ds_bpermute_b32 v31, v37, v17
	s_waitcnt lgkmcnt(0)
	v_add_f32_e32 v77, v17, v31
	v_lshl_add_u64 v[86:87], s[90:91], 0, v[20:21]
	s_branch .LBB0_116
